# S5 pass-1 end state by blocked Horner in the MFMA register layout (no lane transposes), one cross-row reduction per item
# baseline (speedup 1.0000x reference)
; DI void s5_pass1_item(const Params& P, int bitem, unsigned char* smem) {
;     int tid_ = threadIdx.x; asm volatile("" : "+v"(tid_));
;     unsigned char* ws = P.ws; const int tid = tid_, wid = tid >> 6, lane = tid & 63, r = lane & 15, q = lane >> 4;
;     const int item = bitem * 8 + wid, ch = item & 31, grp = (item >> 5) & 63, b = item >> 11;
;     const bf16_t* proj = (const bf16_t*)(ws + WS_PROJ); const float* sm = (const float*)(ws + WS_SMALL);
;     float* buf = (float*)smem + wid * 2176;
;     const bf16_t* tb = (const bf16_t*)(sm + SM_BB);
;     bf16x8 af[8];
; #pragma unroll
;     for (int pt = 0; pt < 8; ++pt) af[pt] = *(const bf16x8*)(tb + (grp * 128 + 16 * pt + r) * 32 + 8 * q);
;     const f32x4 ab = *(const f32x4*)(sm + SM_AB + (grp * 64 + lane) * 4);
;     const bf16_t* ubase = proj + (size_t)(b * TT + ch * 64) * NPROJ + C_SSM + grp * 16;
;     float xr = 0.f, xi = 0.f;
;     bf16x8 ubs[4];
; #pragma unroll
;     for (int sub = 0; sub < 4; ++sub) ubs[sub] = *(const bf16x8*)(ubase + (size_t)(sub * 16 + r) * NPROJ + 8 * (q & 1));
.Ls5p1_start:
	v_readlane_b32 s74, v245, 7
	v_readlane_b32 s75, v245, 8
	v_lshrrev_b32_e32 v1, 6, v206
	v_and_b32_e32 v2, 63, v206
	v_and_b32_e32 v3, 15, v206
	v_readfirstlane_b32 s23, v1
	v_bfe_u32 v4, v206, 4, 2
	s_sub_i32 s2, s71, 0xfe
	s_lshr_b32 s24, s2, 2
	s_and_b32 s25, s2, 3
	s_lshl_b32 s25, s25, 3
	s_add_i32 s25, s25, s23
	v_and_b32_e32 v5, 1, v4
	v_lshlrev_b32_e32 v5, 4, v5
	s_movk_i32 s3, 0x1e00
	v_mad_u32_u24 v83, v3, s3, v5
	v_lshlrev_b32_e32 v84, 3, v2
	v_cmp_eq_u32_e64 s[50:51], 0, v4
	v_cmp_eq_u32_e64 s[52:53], 1, v4
	v_cmp_eq_u32_e64 s[54:55], 2, v4
	s_lshl_b32 s4, s24, 13
	s_add_u32 s6, s74, 0x9f20400
	s_addc_u32 s7, s75, 0
	s_add_u32 s6, s6, s4
	s_addc_u32 s7, s7, 0
	s_add_u32 s8, s6, 0x1000
	s_addc_u32 s9, s7, 0
	v_lshlrev_b32_e32 v5, 6, v3
	v_lshl_add_u32 v5, v4, 4, v5
	global_load_dwordx4 v[8:11], v5, s[6:7] offset:0
	global_load_dwordx4 v[12:15], v5, s[6:7] offset:1024
	global_load_dwordx4 v[16:19], v5, s[6:7] offset:2048
	global_load_dwordx4 v[20:23], v5, s[6:7] offset:3072
	global_load_dwordx4 v[24:27], v5, s[8:9] offset:0
	global_load_dwordx4 v[28:31], v5, s[8:9] offset:1024
	global_load_dwordx4 v[32:35], v5, s[8:9] offset:2048
	global_load_dwordx4 v[36:39], v5, s[8:9] offset:3072
	s_lshl_b32 s4, s24, 10
	s_add_u32 s10, s74, 0x9f10400
	s_addc_u32 s11, s75, 0
	s_add_u32 s10, s10, s4
	s_addc_u32 s11, s11, 0
	v_lshlrev_b32_e32 v6, 4, v3
	global_load_dwordx2 v[72:73], v6, s[10:11] offset:0
	global_load_dwordx2 v[74:75], v6, s[10:11] offset:256
	global_load_dwordx2 v[76:77], v6, s[10:11] offset:512
	global_load_dwordx2 v[78:79], v6, s[10:11] offset:768
	s_mul_i32 s4, s25, 0x78000
	s_lshl_b32 s5, s24, 5
	s_add_i32 s4, s4, s5
	s_add_i32 s4, s4, 0xf911430
	s_add_u32 s28, s74, s4
	s_addc_u32 s29, s75, 0
	s_lshl_b32 s4, s24, 5
	s_add_i32 s4, s4, s25
	s_lshl_b32 s4, s4, 9
	s_add_i32 s4, s4, 0xa110000
	s_add_u32 s30, s74, s4
	s_addc_u32 s31, s75, 0
	s_add_u32 s40, s28, 0x0
	s_addc_u32 s41, s29, 0
	s_add_u32 s42, s28, 0x1e000
	s_addc_u32 s43, s29, 0
	s_add_u32 s44, s28, 0x3c000
	s_addc_u32 s45, s29, 0
	s_add_u32 s46, s28, 0x5a000
	s_addc_u32 s47, s29, 0
	global_load_dwordx4 v[120:123], v83, s[40:41]
	global_load_dwordx4 v[124:127], v83, s[42:43]
	global_load_dwordx4 v[128:131], v83, s[44:45]
	global_load_dwordx4 v[132:135], v83, s[46:47]
	s_mov_b32 s26, 0
	s_waitcnt vmcnt(0)
	v_mov_b32_e32 v40, v72
	v_mov_b32_e32 v44, v73
	v_mov_b32_e32 v48, v72
	v_mov_b32_e32 v52, v73
	v_mul_f32_e32 v194, v52, v52
	v_mul_f32_e32 v195, v48, v52
	v_fma_f32 v48, v48, v48, -v194
	v_add_f32_e32 v52, v195, v195
	v_mul_f32_e32 v194, v52, v52
	v_mul_f32_e32 v195, v48, v52
	v_fma_f32 v48, v48, v48, -v194
	v_add_f32_e32 v52, v195, v195
	v_mov_b32_e32 v196, v48
	v_mov_b32_e32 v197, v52
	v_mul_f32_e32 v194, v52, v52
	v_mul_f32_e32 v195, v48, v52
	v_fma_f32 v48, v48, v48, -v194
	v_add_f32_e32 v52, v195, v195
	v_mov_b32_e32 v198, v48
	v_mov_b32_e32 v199, v52
	v_mul_f32_e32 v194, v199, v197
	v_mul_f32_e32 v195, v199, v196
	v_fma_f32 v56, v198, v196, -v194
	v_fma_f32 v60, v198, v197, v195
	v_mul_f32_e32 v194, v52, v52
	v_mul_f32_e32 v195, v48, v52
	v_fma_f32 v48, v48, v48, -v194
	v_add_f32_e32 v52, v195, v195
	v_cndmask_b32_e64 v56, v56, v198, s[52:53]
	v_cndmask_b32_e64 v60, v60, v199, s[52:53]
	v_cndmask_b32_e64 v56, v56, v196, s[54:55]
	v_cndmask_b32_e64 v60, v60, v197, s[54:55]
	v_mov_b32_e32 v41, v74
	v_mov_b32_e32 v45, v75
	v_mov_b32_e32 v49, v74
	v_mov_b32_e32 v53, v75
	v_mul_f32_e32 v194, v53, v53
	v_mul_f32_e32 v195, v49, v53
	v_fma_f32 v49, v49, v49, -v194
	v_add_f32_e32 v53, v195, v195
	v_mul_f32_e32 v194, v53, v53
	v_mul_f32_e32 v195, v49, v53
	v_fma_f32 v49, v49, v49, -v194
	v_add_f32_e32 v53, v195, v195
	v_mov_b32_e32 v196, v49
	v_mov_b32_e32 v197, v53
	v_mul_f32_e32 v194, v53, v53
	v_mul_f32_e32 v195, v49, v53
	v_fma_f32 v49, v49, v49, -v194
	v_add_f32_e32 v53, v195, v195
	v_mov_b32_e32 v198, v49
	v_mov_b32_e32 v199, v53
	v_mul_f32_e32 v194, v199, v197
	v_mul_f32_e32 v195, v199, v196
	v_fma_f32 v57, v198, v196, -v194
	v_fma_f32 v61, v198, v197, v195
	v_mul_f32_e32 v194, v53, v53
	v_mul_f32_e32 v195, v49, v53
	v_fma_f32 v49, v49, v49, -v194
	v_add_f32_e32 v53, v195, v195
	v_cndmask_b32_e64 v57, v57, v198, s[52:53]
	v_cndmask_b32_e64 v61, v61, v199, s[52:53]
	v_cndmask_b32_e64 v57, v57, v196, s[54:55]
	v_cndmask_b32_e64 v61, v61, v197, s[54:55]
	v_mov_b32_e32 v42, v76
	v_mov_b32_e32 v46, v77
	v_mov_b32_e32 v50, v76
	v_mov_b32_e32 v54, v77
	v_mul_f32_e32 v194, v54, v54
	v_mul_f32_e32 v195, v50, v54
	v_fma_f32 v50, v50, v50, -v194
	v_add_f32_e32 v54, v195, v195
	v_mul_f32_e32 v194, v54, v54
	v_mul_f32_e32 v195, v50, v54
	v_fma_f32 v50, v50, v50, -v194
	v_add_f32_e32 v54, v195, v195
	v_mov_b32_e32 v196, v50
	v_mov_b32_e32 v197, v54
	v_mul_f32_e32 v194, v54, v54
	v_mul_f32_e32 v195, v50, v54
	v_fma_f32 v50, v50, v50, -v194
	v_add_f32_e32 v54, v195, v195
	v_mov_b32_e32 v198, v50
	v_mov_b32_e32 v199, v54
	v_mul_f32_e32 v194, v199, v197
	v_mul_f32_e32 v195, v199, v196
	v_fma_f32 v58, v198, v196, -v194
	v_fma_f32 v62, v198, v197, v195
	v_mul_f32_e32 v194, v54, v54
	v_mul_f32_e32 v195, v50, v54
	v_fma_f32 v50, v50, v50, -v194
	v_add_f32_e32 v54, v195, v195
	v_cndmask_b32_e64 v58, v58, v198, s[52:53]
	v_cndmask_b32_e64 v62, v62, v199, s[52:53]
	v_cndmask_b32_e64 v58, v58, v196, s[54:55]
	v_cndmask_b32_e64 v62, v62, v197, s[54:55]
	v_mov_b32_e32 v43, v78
	v_mov_b32_e32 v47, v79
	v_mov_b32_e32 v51, v78
	v_mov_b32_e32 v55, v79
	v_mul_f32_e32 v194, v55, v55
	v_mul_f32_e32 v195, v51, v55
	v_fma_f32 v51, v51, v51, -v194
	v_add_f32_e32 v55, v195, v195
	v_mul_f32_e32 v194, v55, v55
	v_mul_f32_e32 v195, v51, v55
	v_fma_f32 v51, v51, v51, -v194
	v_add_f32_e32 v55, v195, v195
	v_mov_b32_e32 v196, v51
	v_mov_b32_e32 v197, v55
	v_mul_f32_e32 v194, v55, v55
	v_mul_f32_e32 v195, v51, v55
	v_fma_f32 v51, v51, v51, -v194
	v_add_f32_e32 v55, v195, v195
	v_mov_b32_e32 v198, v51
	v_mov_b32_e32 v199, v55
	v_mul_f32_e32 v194, v199, v197
	v_mul_f32_e32 v195, v199, v196
	v_fma_f32 v59, v198, v196, -v194
	v_fma_f32 v63, v198, v197, v195
	v_mul_f32_e32 v194, v55, v55
	v_mul_f32_e32 v195, v51, v55
	v_fma_f32 v51, v51, v51, -v194
	v_add_f32_e32 v55, v195, v195
	v_cndmask_b32_e64 v59, v59, v198, s[52:53]
	v_cndmask_b32_e64 v63, v63, v199, s[52:53]
	v_cndmask_b32_e64 v59, v59, v196, s[54:55]
	v_cndmask_b32_e64 v63, v63, v197, s[54:55]
	s_or_b64 s[56:57], s[50:51], s[52:53]
	s_or_b64 s[56:57], s[56:57], s[54:55]
	v_mov_b32_e32 v198, 1.0
	v_mov_b32_e32 v199, 0
	v_cndmask_b32_e64 v56, v198, v56, s[56:57]
	v_cndmask_b32_e64 v60, v199, v60, s[56:57]
	v_cndmask_b32_e64 v57, v198, v57, s[56:57]
	v_cndmask_b32_e64 v61, v199, v61, s[56:57]
	v_cndmask_b32_e64 v58, v198, v58, s[56:57]
	v_cndmask_b32_e64 v62, v199, v62, s[56:57]
	v_cndmask_b32_e64 v59, v198, v59, s[56:57]
	v_cndmask_b32_e64 v63, v199, v63, s[56:57]
; DI void s5_bu16(const bf16x8 ub, const bf16x8 (&af)[8], float* buf, int r, int q) {
; #pragma unroll
;     for (int pt = 0; pt < 8; ++pt) { f32x4 d = {0.f, 0.f, 0.f, 0.f}; d = __builtin_amdgcn_mfma_f32_16x16x32_bf16(af[pt], ub, d, 0, 0, 0);
; #pragma unroll
;         for (int j = 0; j < 4; ++j) buf[(16 * pt + 4 * q + j) * 17 + r] = d[j]; }
; DI void s5_pass1_item(const Params& P, int bitem, unsigned char* smem) {
;     ...
;     float xr = 0.f, xi = 0.f;
;     bf16x8 ubs[4];
; #pragma unroll
;     for (int sub = 0; sub < 4; ++sub) ubs[sub] = *(const bf16x8*)(ubase + (size_t)(sub * 16 + r) * NPROJ + 8 * (q & 1));
; #pragma unroll
;     for (int sub = 0; sub < 4; ++sub) {
;         s5_bu16(ubs[sub], af, buf, r, q);
;         asm volatile("s_waitcnt lgkmcnt(0)" ::: "memory");
; #pragma unroll
;         for (int tt = 0; tt < 16; ++tt) { const float bur = buf[lane * 17 + tt], bui = buf[(64 + lane) * 17 + tt];
;             const float nxr = ab[0] * xr - ab[1] * xi + bur, nxi = ab[0] * xi + ab[1] * xr + bui; xr = nxr; xi = nxi; }
.Ls5p1_round:
	s_waitcnt vmcnt(1)
	v_mov_b32_e32 v88, v120
	v_mov_b32_e32 v89, v121
	v_mov_b32_e32 v90, v122
	v_mov_b32_e32 v91, v123
	v_mov_b32_e32 v92, v124
	v_mov_b32_e32 v93, v125
	v_mov_b32_e32 v94, v126
	v_mov_b32_e32 v95, v127
	v_mov_b32_e32 v96, v128
	v_mov_b32_e32 v97, v129
	v_mov_b32_e32 v98, v130
	v_mov_b32_e32 v99, v131
	v_mov_b32_e32 v100, v132
	v_mov_b32_e32 v101, v133
	v_mov_b32_e32 v102, v134
	v_mov_b32_e32 v103, v135
	s_add_u32 s28, s28, 0xf00000
	s_addc_u32 s29, s29, 0
	s_add_u32 s40, s28, 0x0
	s_addc_u32 s41, s29, 0
	s_add_u32 s42, s28, 0x1e000
	s_addc_u32 s43, s29, 0
	s_add_u32 s44, s28, 0x3c000
	s_addc_u32 s45, s29, 0
	s_add_u32 s46, s28, 0x5a000
	s_addc_u32 s47, s29, 0
	global_load_dwordx4 v[120:123], v83, s[40:41]
	global_load_dwordx4 v[124:127], v83, s[42:43]
	global_load_dwordx4 v[128:131], v83, s[44:45]
	global_load_dwordx4 v[132:135], v83, s[46:47]
	v_mov_b32_e32 v64, 0
	v_mov_b32_e32 v68, 0
	v_mov_b32_e32 v65, 0
	v_mov_b32_e32 v69, 0
	v_mov_b32_e32 v66, 0
	v_mov_b32_e32 v70, 0
	v_mov_b32_e32 v67, 0
	v_mov_b32_e32 v71, 0
	v_mfma_f32_16x16x32_bf16 v[160:163], v[88:91], v[8:11], 0
	v_mfma_f32_16x16x32_bf16 v[164:167], v[88:91], v[12:15], 0
	v_mfma_f32_16x16x32_bf16 v[168:171], v[88:91], v[16:19], 0
	v_mfma_f32_16x16x32_bf16 v[172:175], v[88:91], v[20:23], 0
	v_mfma_f32_16x16x32_bf16 v[176:179], v[88:91], v[24:27], 0
	v_mfma_f32_16x16x32_bf16 v[180:183], v[88:91], v[28:31], 0
	v_mfma_f32_16x16x32_bf16 v[184:187], v[88:91], v[32:35], 0
	v_mfma_f32_16x16x32_bf16 v[188:191], v[88:91], v[36:39], 0
	s_nop 7
	v_fma_f32 v194, -v44, v176, v161
	v_fma_f32 v195, v44, v160, v177
	v_fma_f32 v196, v40, v160, v194
	v_fma_f32 v197, v40, v176, v195
	v_fma_f32 v194, -v44, v197, v162
	v_fma_f32 v195, v44, v196, v178
	v_fma_f32 v196, v40, v196, v194
	v_fma_f32 v197, v40, v197, v195
	v_fma_f32 v194, -v44, v197, v163
	v_fma_f32 v195, v44, v196, v179
	v_fma_f32 v196, v40, v196, v194
	v_fma_f32 v197, v40, v197, v195
	v_fma_f32 v194, -v52, v68, v196
	v_fma_f32 v195, v52, v64, v197
	v_fma_f32 v64, v48, v64, v194
	v_fma_f32 v68, v48, v68, v195
	v_fma_f32 v194, -v45, v180, v165
	v_fma_f32 v195, v45, v164, v181
	v_fma_f32 v196, v41, v164, v194
	v_fma_f32 v197, v41, v180, v195
	v_fma_f32 v194, -v45, v197, v166
	v_fma_f32 v195, v45, v196, v182
	v_fma_f32 v196, v41, v196, v194
	v_fma_f32 v197, v41, v197, v195
	v_fma_f32 v194, -v45, v197, v167
	v_fma_f32 v195, v45, v196, v183
	v_fma_f32 v196, v41, v196, v194
	v_fma_f32 v197, v41, v197, v195
	v_fma_f32 v194, -v53, v69, v196
	v_fma_f32 v195, v53, v65, v197
	v_fma_f32 v65, v49, v65, v194
	v_fma_f32 v69, v49, v69, v195
	v_fma_f32 v194, -v46, v184, v169
	v_fma_f32 v195, v46, v168, v185
	v_fma_f32 v196, v42, v168, v194
	v_fma_f32 v197, v42, v184, v195
	v_fma_f32 v194, -v46, v197, v170
	v_fma_f32 v195, v46, v196, v186
	v_fma_f32 v196, v42, v196, v194
	v_fma_f32 v197, v42, v197, v195
	v_fma_f32 v194, -v46, v197, v171
	v_fma_f32 v195, v46, v196, v187
	v_fma_f32 v196, v42, v196, v194
	v_fma_f32 v197, v42, v197, v195
	v_fma_f32 v194, -v54, v70, v196
	v_fma_f32 v195, v54, v66, v197
	v_fma_f32 v66, v50, v66, v194
	v_fma_f32 v70, v50, v70, v195
	v_fma_f32 v194, -v47, v188, v173
	v_fma_f32 v195, v47, v172, v189
	v_fma_f32 v196, v43, v172, v194
	v_fma_f32 v197, v43, v188, v195
	v_fma_f32 v194, -v47, v197, v174
	v_fma_f32 v195, v47, v196, v190
	v_fma_f32 v196, v43, v196, v194
	v_fma_f32 v197, v43, v197, v195
	v_fma_f32 v194, -v47, v197, v175
	v_fma_f32 v195, v47, v196, v191
	v_fma_f32 v196, v43, v196, v194
	v_fma_f32 v197, v43, v197, v195
	v_fma_f32 v194, -v55, v71, v196
	v_fma_f32 v195, v55, v67, v197
	v_fma_f32 v67, v51, v67, v194
	v_fma_f32 v71, v51, v71, v195
	v_mfma_f32_16x16x32_bf16 v[160:163], v[92:95], v[8:11], 0
	v_mfma_f32_16x16x32_bf16 v[164:167], v[92:95], v[12:15], 0
	v_mfma_f32_16x16x32_bf16 v[168:171], v[92:95], v[16:19], 0
	v_mfma_f32_16x16x32_bf16 v[172:175], v[92:95], v[20:23], 0
	v_mfma_f32_16x16x32_bf16 v[176:179], v[92:95], v[24:27], 0
	v_mfma_f32_16x16x32_bf16 v[180:183], v[92:95], v[28:31], 0
	v_mfma_f32_16x16x32_bf16 v[184:187], v[92:95], v[32:35], 0
	v_mfma_f32_16x16x32_bf16 v[188:191], v[92:95], v[36:39], 0
	s_nop 7
	v_fma_f32 v194, -v44, v176, v161
	v_fma_f32 v195, v44, v160, v177
	v_fma_f32 v196, v40, v160, v194
	v_fma_f32 v197, v40, v176, v195
	v_fma_f32 v194, -v44, v197, v162
	v_fma_f32 v195, v44, v196, v178
	v_fma_f32 v196, v40, v196, v194
	v_fma_f32 v197, v40, v197, v195
	v_fma_f32 v194, -v44, v197, v163
	v_fma_f32 v195, v44, v196, v179
	v_fma_f32 v196, v40, v196, v194
	v_fma_f32 v197, v40, v197, v195
	v_fma_f32 v194, -v52, v68, v196
	v_fma_f32 v195, v52, v64, v197
	v_fma_f32 v64, v48, v64, v194
	v_fma_f32 v68, v48, v68, v195
	v_fma_f32 v194, -v45, v180, v165
	v_fma_f32 v195, v45, v164, v181
	v_fma_f32 v196, v41, v164, v194
	v_fma_f32 v197, v41, v180, v195
	v_fma_f32 v194, -v45, v197, v166
	v_fma_f32 v195, v45, v196, v182
	v_fma_f32 v196, v41, v196, v194
	v_fma_f32 v197, v41, v197, v195
	v_fma_f32 v194, -v45, v197, v167
	v_fma_f32 v195, v45, v196, v183
	v_fma_f32 v196, v41, v196, v194
	v_fma_f32 v197, v41, v197, v195
	v_fma_f32 v194, -v53, v69, v196
	v_fma_f32 v195, v53, v65, v197
	v_fma_f32 v65, v49, v65, v194
	v_fma_f32 v69, v49, v69, v195
	v_fma_f32 v194, -v46, v184, v169
	v_fma_f32 v195, v46, v168, v185
	v_fma_f32 v196, v42, v168, v194
	v_fma_f32 v197, v42, v184, v195
	v_fma_f32 v194, -v46, v197, v170
	v_fma_f32 v195, v46, v196, v186
	v_fma_f32 v196, v42, v196, v194
	v_fma_f32 v197, v42, v197, v195
	v_fma_f32 v194, -v46, v197, v171
	v_fma_f32 v195, v46, v196, v187
	v_fma_f32 v196, v42, v196, v194
	v_fma_f32 v197, v42, v197, v195
	v_fma_f32 v194, -v54, v70, v196
; DI void s5_pass1_item(const Params& P, int bitem, unsigned char* smem) {
;     ...
;     for (int sub = 0; sub < 4; ++sub) {
;         s5_bu16(ubs[sub], af, buf, r, q);
;         asm volatile("s_waitcnt lgkmcnt(0)" ::: "memory");
; #pragma unroll
;         for (int tt = 0; tt < 16; ++tt) { const float bur = buf[lane * 17 + tt], bui = buf[(64 + lane) * 17 + tt];
;             const float nxr = ab[0] * xr - ab[1] * xi + bur, nxi = ab[0] * xi + ab[1] * xr + bui; xr = nxr; xi = nxi; }
	v_fma_f32 v195, v54, v66, v197
	v_fma_f32 v66, v50, v66, v194
	v_fma_f32 v70, v50, v70, v195
	v_fma_f32 v194, -v47, v188, v173
	v_fma_f32 v195, v47, v172, v189
	v_fma_f32 v196, v43, v172, v194
	v_fma_f32 v197, v43, v188, v195
	v_fma_f32 v194, -v47, v197, v174
	v_fma_f32 v195, v47, v196, v190
	v_fma_f32 v196, v43, v196, v194
	v_fma_f32 v197, v43, v197, v195
	v_fma_f32 v194, -v47, v197, v175
	v_fma_f32 v195, v47, v196, v191
	v_fma_f32 v196, v43, v196, v194
	v_fma_f32 v197, v43, v197, v195
	v_fma_f32 v194, -v55, v71, v196
	v_fma_f32 v195, v55, v67, v197
	v_fma_f32 v67, v51, v67, v194
	v_fma_f32 v71, v51, v71, v195
	v_mfma_f32_16x16x32_bf16 v[160:163], v[96:99], v[8:11], 0
	v_mfma_f32_16x16x32_bf16 v[164:167], v[96:99], v[12:15], 0
	v_mfma_f32_16x16x32_bf16 v[168:171], v[96:99], v[16:19], 0
	v_mfma_f32_16x16x32_bf16 v[172:175], v[96:99], v[20:23], 0
	v_mfma_f32_16x16x32_bf16 v[176:179], v[96:99], v[24:27], 0
	v_mfma_f32_16x16x32_bf16 v[180:183], v[96:99], v[28:31], 0
	v_mfma_f32_16x16x32_bf16 v[184:187], v[96:99], v[32:35], 0
	v_mfma_f32_16x16x32_bf16 v[188:191], v[96:99], v[36:39], 0
	s_nop 7
	v_fma_f32 v194, -v44, v176, v161
	v_fma_f32 v195, v44, v160, v177
	v_fma_f32 v196, v40, v160, v194
	v_fma_f32 v197, v40, v176, v195
	v_fma_f32 v194, -v44, v197, v162
	v_fma_f32 v195, v44, v196, v178
	v_fma_f32 v196, v40, v196, v194
	v_fma_f32 v197, v40, v197, v195
	v_fma_f32 v194, -v44, v197, v163
	v_fma_f32 v195, v44, v196, v179
	v_fma_f32 v196, v40, v196, v194
	v_fma_f32 v197, v40, v197, v195
	v_fma_f32 v194, -v52, v68, v196
	v_fma_f32 v195, v52, v64, v197
	v_fma_f32 v64, v48, v64, v194
	v_fma_f32 v68, v48, v68, v195
	v_fma_f32 v194, -v45, v180, v165
	v_fma_f32 v195, v45, v164, v181
	v_fma_f32 v196, v41, v164, v194
	v_fma_f32 v197, v41, v180, v195
	v_fma_f32 v194, -v45, v197, v166
	v_fma_f32 v195, v45, v196, v182
	v_fma_f32 v196, v41, v196, v194
	v_fma_f32 v197, v41, v197, v195
	v_fma_f32 v194, -v45, v197, v167
	v_fma_f32 v195, v45, v196, v183
	v_fma_f32 v196, v41, v196, v194
	v_fma_f32 v197, v41, v197, v195
	v_fma_f32 v194, -v53, v69, v196
	v_fma_f32 v195, v53, v65, v197
	v_fma_f32 v65, v49, v65, v194
	v_fma_f32 v69, v49, v69, v195
	v_fma_f32 v194, -v46, v184, v169
	v_fma_f32 v195, v46, v168, v185
	v_fma_f32 v196, v42, v168, v194
	v_fma_f32 v197, v42, v184, v195
	v_fma_f32 v194, -v46, v197, v170
	v_fma_f32 v195, v46, v196, v186
	v_fma_f32 v196, v42, v196, v194
	v_fma_f32 v197, v42, v197, v195
	v_fma_f32 v194, -v46, v197, v171
	v_fma_f32 v195, v46, v196, v187
	v_fma_f32 v196, v42, v196, v194
	v_fma_f32 v197, v42, v197, v195
	v_fma_f32 v194, -v54, v70, v196
	v_fma_f32 v195, v54, v66, v197
	v_fma_f32 v66, v50, v66, v194
	v_fma_f32 v70, v50, v70, v195
	v_fma_f32 v194, -v47, v188, v173
	v_fma_f32 v195, v47, v172, v189
	v_fma_f32 v196, v43, v172, v194
	v_fma_f32 v197, v43, v188, v195
	v_fma_f32 v194, -v47, v197, v174
	v_fma_f32 v195, v47, v196, v190
	v_fma_f32 v196, v43, v196, v194
	v_fma_f32 v197, v43, v197, v195
	v_fma_f32 v194, -v47, v197, v175
	v_fma_f32 v195, v47, v196, v191
	v_fma_f32 v196, v43, v196, v194
	v_fma_f32 v197, v43, v197, v195
	v_fma_f32 v194, -v55, v71, v196
	v_fma_f32 v195, v55, v67, v197
	v_fma_f32 v67, v51, v67, v194
	v_fma_f32 v71, v51, v71, v195
	v_mfma_f32_16x16x32_bf16 v[160:163], v[100:103], v[8:11], 0
	v_mfma_f32_16x16x32_bf16 v[164:167], v[100:103], v[12:15], 0
	v_mfma_f32_16x16x32_bf16 v[168:171], v[100:103], v[16:19], 0
	v_mfma_f32_16x16x32_bf16 v[172:175], v[100:103], v[20:23], 0
	v_mfma_f32_16x16x32_bf16 v[176:179], v[100:103], v[24:27], 0
	v_mfma_f32_16x16x32_bf16 v[180:183], v[100:103], v[28:31], 0
	v_mfma_f32_16x16x32_bf16 v[184:187], v[100:103], v[32:35], 0
	v_mfma_f32_16x16x32_bf16 v[188:191], v[100:103], v[36:39], 0
	s_nop 7
	v_fma_f32 v194, -v44, v176, v161
	v_fma_f32 v195, v44, v160, v177
	v_fma_f32 v196, v40, v160, v194
	v_fma_f32 v197, v40, v176, v195
	v_fma_f32 v194, -v44, v197, v162
	v_fma_f32 v195, v44, v196, v178
	v_fma_f32 v196, v40, v196, v194
	v_fma_f32 v197, v40, v197, v195
	v_fma_f32 v194, -v44, v197, v163
	v_fma_f32 v195, v44, v196, v179
	v_fma_f32 v196, v40, v196, v194
	v_fma_f32 v197, v40, v197, v195
; DI void s5_pass1_item(const Params& P, int bitem, unsigned char* smem) {
;     ...
;     for (int sub = 0; sub < 4; ++sub) {
;         s5_bu16(ubs[sub], af, buf, r, q);
;         asm volatile("s_waitcnt lgkmcnt(0)" ::: "memory");
; #pragma unroll
;         for (int tt = 0; tt < 16; ++tt) { const float bur = buf[lane * 17 + tt], bui = buf[(64 + lane) * 17 + tt];
;             const float nxr = ab[0] * xr - ab[1] * xi + bur, nxi = ab[0] * xi + ab[1] * xr + bui; xr = nxr; xi = nxi; }
;         asm volatile("s_waitcnt lgkmcnt(0)" ::: "memory");
;     }
;     f32x2_t e = {xr, xi};
;     *(f32x2_t*)(ws + WS_S5END + ((size_t)((b * 64 + grp) * 32 + ch) * 64 + lane) * 8) = e;
	v_fma_f32 v194, -v52, v68, v196
	v_fma_f32 v195, v52, v64, v197
	v_fma_f32 v64, v48, v64, v194
	v_fma_f32 v68, v48, v68, v195
	v_fma_f32 v194, -v45, v180, v165
	v_fma_f32 v195, v45, v164, v181
	v_fma_f32 v196, v41, v164, v194
	v_fma_f32 v197, v41, v180, v195
	v_fma_f32 v194, -v45, v197, v166
	v_fma_f32 v195, v45, v196, v182
	v_fma_f32 v196, v41, v196, v194
	v_fma_f32 v197, v41, v197, v195
	v_fma_f32 v194, -v45, v197, v167
	v_fma_f32 v195, v45, v196, v183
	v_fma_f32 v196, v41, v196, v194
	v_fma_f32 v197, v41, v197, v195
	v_fma_f32 v194, -v53, v69, v196
	v_fma_f32 v195, v53, v65, v197
	v_fma_f32 v65, v49, v65, v194
	v_fma_f32 v69, v49, v69, v195
	v_fma_f32 v194, -v46, v184, v169
	v_fma_f32 v195, v46, v168, v185
	v_fma_f32 v196, v42, v168, v194
	v_fma_f32 v197, v42, v184, v195
	v_fma_f32 v194, -v46, v197, v170
	v_fma_f32 v195, v46, v196, v186
	v_fma_f32 v196, v42, v196, v194
	v_fma_f32 v197, v42, v197, v195
	v_fma_f32 v194, -v46, v197, v171
	v_fma_f32 v195, v46, v196, v187
	v_fma_f32 v196, v42, v196, v194
	v_fma_f32 v197, v42, v197, v195
	v_fma_f32 v194, -v54, v70, v196
	v_fma_f32 v195, v54, v66, v197
	v_fma_f32 v66, v50, v66, v194
	v_fma_f32 v70, v50, v70, v195
	v_fma_f32 v194, -v47, v188, v173
	v_fma_f32 v195, v47, v172, v189
	v_fma_f32 v196, v43, v172, v194
	v_fma_f32 v197, v43, v188, v195
	v_fma_f32 v194, -v47, v197, v174
	v_fma_f32 v195, v47, v196, v190
	v_fma_f32 v196, v43, v196, v194
	v_fma_f32 v197, v43, v197, v195
	v_fma_f32 v194, -v47, v197, v175
	v_fma_f32 v195, v47, v196, v191
	v_fma_f32 v196, v43, v196, v194
	v_fma_f32 v197, v43, v197, v195
	v_fma_f32 v194, -v55, v71, v196
	v_fma_f32 v195, v55, v67, v197
	v_fma_f32 v67, v51, v67, v194
	v_fma_f32 v71, v51, v71, v195
	v_mul_f32_e32 v194, v60, v68
	v_mul_f32_e32 v195, v60, v64
	v_fma_f32 v64, v56, v64, -v194
	v_fma_f32 v68, v56, v68, v195
	v_mul_f32_e32 v194, v61, v69
	v_mul_f32_e32 v195, v61, v65
	v_fma_f32 v65, v57, v65, -v194
	v_fma_f32 v69, v57, v69, v195
	v_mul_f32_e32 v194, v62, v70
	v_mul_f32_e32 v195, v62, v66
	v_fma_f32 v66, v58, v66, -v194
	v_fma_f32 v70, v58, v70, v195
	v_mul_f32_e32 v194, v63, v71
	v_mul_f32_e32 v195, v63, v67
	v_fma_f32 v67, v59, v67, -v194
	v_fma_f32 v71, v59, v71, v195
	v_mov_b32_e32 v72, v64
	v_mov_b32_e32 v73, v65
	v_mov_b32_e32 v74, v66
	v_mov_b32_e32 v75, v67
	v_mov_b32_e32 v76, v68
	v_mov_b32_e32 v77, v69
	v_mov_b32_e32 v78, v70
	v_mov_b32_e32 v79, v71
	s_nop 0
	v_permlane32_swap_b32_e32 v64, v72
	v_permlane32_swap_b32_e32 v65, v73
	v_permlane32_swap_b32_e32 v66, v74
	v_permlane32_swap_b32_e32 v67, v75
	v_permlane32_swap_b32_e32 v68, v76
	v_permlane32_swap_b32_e32 v69, v77
	v_permlane32_swap_b32_e32 v70, v78
	v_permlane32_swap_b32_e32 v71, v79
	v_add_f32_e32 v64, v64, v72
	v_add_f32_e32 v65, v65, v73
	v_add_f32_e32 v66, v66, v74
	v_add_f32_e32 v67, v67, v75
	v_add_f32_e32 v68, v68, v76
	v_add_f32_e32 v69, v69, v77
	v_add_f32_e32 v70, v70, v78
	v_add_f32_e32 v71, v71, v79
	v_mov_b32_e32 v72, v64
	v_mov_b32_e32 v73, v65
	v_mov_b32_e32 v74, v66
	v_mov_b32_e32 v75, v67
	v_mov_b32_e32 v76, v68
	v_mov_b32_e32 v77, v69
	v_mov_b32_e32 v78, v70
	v_mov_b32_e32 v79, v71
	s_nop 0
	v_permlane16_swap_b32_e32 v64, v72
	v_permlane16_swap_b32_e32 v65, v73
	v_permlane16_swap_b32_e32 v66, v74
	v_permlane16_swap_b32_e32 v67, v75
	v_permlane16_swap_b32_e32 v68, v76
	v_permlane16_swap_b32_e32 v69, v77
	v_permlane16_swap_b32_e32 v70, v78
	v_permlane16_swap_b32_e32 v71, v79
	v_add_f32_e32 v64, v64, v72
	v_add_f32_e32 v65, v65, v73
	v_add_f32_e32 v66, v66, v74
	v_add_f32_e32 v67, v67, v75
	v_add_f32_e32 v68, v68, v76
	v_add_f32_e32 v69, v69, v77
	v_add_f32_e32 v70, v70, v78
	v_add_f32_e32 v71, v71, v79
	v_cndmask_b32_e64 v192, v67, v66, s[54:55]
	v_cndmask_b32_e64 v193, v71, v70, s[54:55]
	v_cndmask_b32_e64 v192, v192, v65, s[52:53]
	v_cndmask_b32_e64 v193, v193, v69, s[52:53]
	v_cndmask_b32_e64 v192, v192, v64, s[50:51]
	v_cndmask_b32_e64 v193, v193, v68, s[50:51]
	global_store_dwordx2 v84, v[192:193], s[30:31]
	s_add_u32 s30, s30, 0x100000
	s_addc_u32 s31, s31, 0
	s_add_i32 s26, s26, 1
	s_cmp_lt_u32 s26, 8
	s_cbranch_scc1 .Ls5p1_round
	s_waitcnt vmcnt(0)
	s_branch .LBB0_654
